# POST ticket-to-unit mapping interleaves the three unit kinds (q/k/v, z transposes, gMLP) instead of running them in three consecutive blocks
# speedup vs baseline: 1.0146x; 1.0096x over previous
; __device__ __forceinline__ void post_phase(const Params& p, int l, LAS unsigned char* lds, int tid) {
;     ...
;     for (int u = blockIdx.x; u < 272 * 3; ) {
;         const int part = u / 272, ci = u % 272;
;         const bool isx = ci < 256;
;         const int R0 = ci * 128;
;         const int b = isx ? (ci >> 5) : ((ci - 256) >> 1);
;         const int n0 = isx ? (ci & 31) * 128 : ((ci - 256) & 1) * 128;
;         const int t0 = isx ? 256 + n0 : n0;
;         const bf16_t* px = PX + (size_t)R0 * NIN;
;         if (part == 0) {
.LBB0_351:
	s_mul_hi_u32 s0, s11, 0xaaaaaaab
	s_lshr_b32 s0, s0, 1
	s_mul_i32 s1, s0, 3
	s_sub_i32 s1, s11, s1
	s_mulk_i32 s1, 0x110
	s_add_i32 s11, s1, s0
	s_mul_hi_i32 s0, s11, 0x78787879
	s_lshr_b32 s1, s0, 31
	s_ashr_i32 s0, s0, 7
	s_add_i32 s0, s0, s1
	s_mulk_i32 s0, 0x110
	s_sub_i32 s0, s11, s0
	s_cmpk_lt_i32 s0, 0x100
	s_cselect_b64 s[48:49], -1, 0
	s_cmpk_gt_i32 s0, 0xff
	s_mul_i32 s4, s0, 0x38000
	s_cselect_b64 s[94:95], -1, 0
	s_lshl_b32 s10, s0, 7
	s_add_i32 s1, s0, 0xffffff00
	s_ashr_i32 s5, s4, 31
	s_ashr_i32 s7, s0, 5
	s_lshr_b32 s8, s1, 1
	s_and_b32 s6, s10, 0xf80
	s_and_b32 s9, s10, 0x80
	s_lshl_b64 s[0:1], s[4:5], 1
	s_add_u32 s46, s69, s0
	s_addc_u32 s47, s51, s1
	s_add_i32 s0, s11, 0x10f
	s_cmpk_gt_u32 s0, 0x21e
	s_mov_b64 s[0:1], -1
	s_cbranch_scc1 .LBB0_354
	s_andn2_b64 vcc, exec, s[0:1]
	s_cbranch_vccz .LBB0_378
